# v21 + remaining P30 filter-table guard waits removed (2 address-path + 46 i==L branch vmcnt(0)): all table loads of a spectra call now in flight together
# baseline (speedup 1.0000x reference)
; template <int M>
; __device__ __forceinline__ void hy_filter_spectra(LAS vf2* X, const int tid_in, const float* hfa, const float* hba, const float* hfb, const float* hbb, vf2* FSa, vf2* FSb) {
;     ...
;         for (int j = 0; j < N / NTHR; ++j) { const int i = tid + NTHR * j; if (i < L) { va[j] = hfa[i]; vb[j] = hfb[i]; } else if (i == L) { va[j] = 0.f; vb[j] = 0.f; } else { va[j] = hba[N - i]; vb[j] = hbb[N - i]; } }
.LBB0_2763:
	s_andn2_saveexec_b64 s[2:3], s[2:3]
	s_cbranch_execz .LBB0_2765
	v_mov_b32_e32 v65, 0

; template <int M>
; __device__ __forceinline__ void hy_filter_spectra(LAS vf2* X, const int tid_in, const float* hfa, const float* hba, const float* hfb, const float* hbb, vf2* FSa, vf2* FSb) {
;     ...
;         for (int j = 0; j < N / NTHR; ++j) { const int i = tid + NTHR * j; if (i < L) { va[j] = hfa[i]; vb[j] = hfb[i]; } else if (i == L) { va[j] = 0.f; vb[j] = 0.f; } else { va[j] = hba[N - i]; vb[j] = hbb[N - i]; } }
.LBB0_2771:
	s_andn2_saveexec_b64 s[2:3], s[2:3]
	s_cbranch_execz .LBB0_2773
	v_mov_b32_e32 v33, 0

; template <int M>
; __device__ __forceinline__ void hy_filter_spectra(LAS vf2* X, const int tid_in, const float* hfa, const float* hba, const float* hfb, const float* hbb, vf2* FSa, vf2* FSb) {
;     ...
;         for (int j = 0; j < N / NTHR; ++j) { const int i = tid + NTHR * j; if (i < L) { va[j] = hfa[i]; vb[j] = hfb[i]; } else if (i == L) { va[j] = 0.f; vb[j] = 0.f; } else { va[j] = hba[N - i]; vb[j] = hbb[N - i]; } }
.LBB0_2774:
	s_andn2_saveexec_b64 s[0:1], s[0:1]
	s_cbranch_execz .LBB0_2776
	v_ashrrev_i32_e32 v67, 31, v66
	v_lshlrev_b64 v[68:69], 2, v[66:67]
	v_lshl_add_u64 v[32:33], s[4:5], 0, v[68:69]
	v_lshl_add_u64 v[68:69], s[58:59], 0, v[68:69]
	global_load_dword v32, v[32:33], off
	s_nop 0
	global_load_dword v33, v[68:69], off

; template <int M>
; __device__ __forceinline__ void hy_filter_spectra(LAS vf2* X, const int tid_in, const float* hfa, const float* hba, const float* hfb, const float* hbb, vf2* FSa, vf2* FSb) {
;     ...
;         for (int j = 0; j < N / NTHR; ++j) { const int i = tid + NTHR * j; if (i < L) { va[j] = hfa[i]; vb[j] = hfb[i]; } else if (i == L) { va[j] = 0.f; vb[j] = 0.f; } else { va[j] = hba[N - i]; vb[j] = hbb[N - i]; } }
.LBB0_2779:
	s_andn2_saveexec_b64 s[2:3], s[2:3]
	s_cbranch_execz .LBB0_2781
	v_mov_b32_e32 v71, 0

; template <int M>
; __device__ __forceinline__ void hy_filter_spectra(LAS vf2* X, const int tid_in, const float* hfa, const float* hba, const float* hfb, const float* hbb, vf2* FSa, vf2* FSb) {
;     ...
;         for (int j = 0; j < N / NTHR; ++j) { const int i = tid + NTHR * j; if (i < L) { va[j] = hfa[i]; vb[j] = hfb[i]; } else if (i == L) { va[j] = 0.f; vb[j] = 0.f; } else { va[j] = hba[N - i]; vb[j] = hbb[N - i]; } }
.LBB0_2787:
	s_andn2_saveexec_b64 s[2:3], s[2:3]
	s_cbranch_execz .LBB0_2789
	v_mov_b32_e32 v75, 0

; template <int M>
; __device__ __forceinline__ void hy_filter_spectra(LAS vf2* X, const int tid_in, const float* hfa, const float* hba, const float* hfb, const float* hbb, vf2* FSa, vf2* FSb) {
;     ...
;         for (int j = 0; j < N / NTHR; ++j) { const int i = tid + NTHR * j; if (i < L) { va[j] = hfa[i]; vb[j] = hfb[i]; } else if (i == L) { va[j] = 0.f; vb[j] = 0.f; } else { va[j] = hba[N - i]; vb[j] = hbb[N - i]; } }
.LBB0_2795:
	s_andn2_saveexec_b64 s[2:3], s[2:3]
	s_cbranch_execz .LBB0_2797
	v_mov_b32_e32 v79, 0

; template <int M>
; __device__ __forceinline__ void hy_filter_spectra(LAS vf2* X, const int tid_in, const float* hfa, const float* hba, const float* hfb, const float* hbb, vf2* FSa, vf2* FSb) {
;     ...
;         for (int j = 0; j < N / NTHR; ++j) { const int i = tid + NTHR * j; if (i < L) { va[j] = hfa[i]; vb[j] = hfb[i]; } else if (i == L) { va[j] = 0.f; vb[j] = 0.f; } else { va[j] = hba[N - i]; vb[j] = hbb[N - i]; } }
.LBB0_2803:
	s_andn2_saveexec_b64 s[2:3], s[2:3]
	s_cbranch_execz .LBB0_2805
	v_mov_b32_e32 v83, 0

; template <int M>
; __device__ __forceinline__ void hy_filter_spectra(LAS vf2* X, const int tid_in, const float* hfa, const float* hba, const float* hfb, const float* hbb, vf2* FSa, vf2* FSb) {
;     ...
;         for (int j = 0; j < N / NTHR; ++j) { const int i = tid + NTHR * j; if (i < L) { va[j] = hfa[i]; vb[j] = hfb[i]; } else if (i == L) { va[j] = 0.f; vb[j] = 0.f; } else { va[j] = hba[N - i]; vb[j] = hbb[N - i]; } }
.LBB0_2811:
	s_andn2_saveexec_b64 s[2:3], s[2:3]
	s_cbranch_execz .LBB0_2813
	v_mov_b32_e32 v87, 0

; template <int M>
; __device__ __forceinline__ void hy_filter_spectra(LAS vf2* X, const int tid_in, const float* hfa, const float* hba, const float* hfb, const float* hbb, vf2* FSa, vf2* FSb) {
;     ...
;         for (int j = 0; j < N / NTHR; ++j) { const int i = tid + NTHR * j; if (i < L) { va[j] = hfa[i]; vb[j] = hfb[i]; } else if (i == L) { va[j] = 0.f; vb[j] = 0.f; } else { va[j] = hba[N - i]; vb[j] = hbb[N - i]; } }
.LBB0_2819:
	s_andn2_saveexec_b64 s[2:3], s[2:3]
	s_cbranch_execz .LBB0_2821
	v_mov_b32_e32 v91, 0

; template <int M>
; __device__ __forceinline__ void hy_filter_spectra(LAS vf2* X, const int tid_in, const float* hfa, const float* hba, const float* hfb, const float* hbb, vf2* FSa, vf2* FSb) {
;     ...
;         for (int j = 0; j < N / NTHR; ++j) { const int i = tid + NTHR * j; if (i < L) { va[j] = hfa[i]; vb[j] = hfb[i]; } else if (i == L) { va[j] = 0.f; vb[j] = 0.f; } else { va[j] = hba[N - i]; vb[j] = hbb[N - i]; } }
.LBB0_2827:
	s_andn2_saveexec_b64 s[2:3], s[2:3]
	s_cbranch_execz .LBB0_2829
	v_mov_b32_e32 v95, 0

; template <int M>
; __device__ __forceinline__ void hy_filter_spectra(LAS vf2* X, const int tid_in, const float* hfa, const float* hba, const float* hfb, const float* hbb, vf2* FSa, vf2* FSb) {
;     ...
;         for (int j = 0; j < N / NTHR; ++j) { const int i = tid + NTHR * j; if (i < L) { va[j] = hfa[i]; vb[j] = hfb[i]; } else if (i == L) { va[j] = 0.f; vb[j] = 0.f; } else { va[j] = hba[N - i]; vb[j] = hbb[N - i]; } }
.LBB0_2835:
	s_andn2_saveexec_b64 s[2:3], s[2:3]
	s_cbranch_execz .LBB0_2837
	v_mov_b32_e32 v99, 0

; template <int M>
; __device__ __forceinline__ void hy_filter_spectra(LAS vf2* X, const int tid_in, const float* hfa, const float* hba, const float* hfb, const float* hbb, vf2* FSa, vf2* FSb) {
;     ...
;         for (int j = 0; j < N / NTHR; ++j) { const int i = tid + NTHR * j; if (i < L) { va[j] = hfa[i]; vb[j] = hfb[i]; } else if (i == L) { va[j] = 0.f; vb[j] = 0.f; } else { va[j] = hba[N - i]; vb[j] = hbb[N - i]; } }
.LBB0_2843:
	s_andn2_saveexec_b64 s[2:3], s[2:3]
	s_cbranch_execz .LBB0_2845
	v_mov_b32_e32 v103, 0

; template <int M>
; __device__ __forceinline__ void hy_filter_spectra(LAS vf2* X, const int tid_in, const float* hfa, const float* hba, const float* hfb, const float* hbb, vf2* FSa, vf2* FSb) {
;     ...
;         for (int j = 0; j < N / NTHR; ++j) { const int i = tid + NTHR * j; if (i < L) { va[j] = hfa[i]; vb[j] = hfb[i]; } else if (i == L) { va[j] = 0.f; vb[j] = 0.f; } else { va[j] = hba[N - i]; vb[j] = hbb[N - i]; } }
.LBB0_2851:
	s_andn2_saveexec_b64 s[2:3], s[2:3]
	s_cbranch_execz .LBB0_2853
	v_mov_b32_e32 v107, 0

; template <int M>
; __device__ __forceinline__ void hy_filter_spectra(LAS vf2* X, const int tid_in, const float* hfa, const float* hba, const float* hfb, const float* hbb, vf2* FSa, vf2* FSb) {
;     ...
;         for (int j = 0; j < N / NTHR; ++j) { const int i = tid + NTHR * j; if (i < L) { va[j] = hfa[i]; vb[j] = hfb[i]; } else if (i == L) { va[j] = 0.f; vb[j] = 0.f; } else { va[j] = hba[N - i]; vb[j] = hbb[N - i]; } }
.LBB0_2859:
	s_andn2_saveexec_b64 s[2:3], s[2:3]
	s_cbranch_execz .LBB0_2861
	v_mov_b32_e32 v111, 0

; template <int M>
; __device__ __forceinline__ void hy_filter_spectra(LAS vf2* X, const int tid_in, const float* hfa, const float* hba, const float* hfb, const float* hbb, vf2* FSa, vf2* FSb) {
;     ...
;         for (int j = 0; j < N / NTHR; ++j) { const int i = tid + NTHR * j; if (i < L) { va[j] = hfa[i]; vb[j] = hfb[i]; } else if (i == L) { va[j] = 0.f; vb[j] = 0.f; } else { va[j] = hba[N - i]; vb[j] = hbb[N - i]; } }
.LBB0_2867:
	s_andn2_saveexec_b64 s[2:3], s[2:3]
	s_cbranch_execz .LBB0_2869
	v_mov_b32_e32 v115, 0

; template <int M>
; __device__ __forceinline__ void hy_filter_spectra(LAS vf2* X, const int tid_in, const float* hfa, const float* hba, const float* hfb, const float* hbb, vf2* FSa, vf2* FSb) {
;     ...
;         for (int j = 0; j < N / NTHR; ++j) { const int i = tid + NTHR * j; if (i < L) { va[j] = hfa[i]; vb[j] = hfb[i]; } else if (i == L) { va[j] = 0.f; vb[j] = 0.f; } else { va[j] = hba[N - i]; vb[j] = hbb[N - i]; } }
.LBB0_2875:
	s_andn2_saveexec_b64 s[2:3], s[2:3]
	s_cbranch_execz .LBB0_2877
	v_mov_b32_e32 v119, 0

; template <int M>
; __device__ __forceinline__ void hy_filter_spectra(LAS vf2* X, const int tid_in, const float* hfa, const float* hba, const float* hfb, const float* hbb, vf2* FSa, vf2* FSb) {
;     ...
;         for (int j = 0; j < N / NTHR; ++j) { const int i = tid + NTHR * j; if (i < L) { va[j] = hfa[i]; vb[j] = hfb[i]; } else if (i == L) { va[j] = 0.f; vb[j] = 0.f; } else { va[j] = hba[N - i]; vb[j] = hbb[N - i]; } }
.LBB0_2883:
	s_andn2_saveexec_b64 s[2:3], s[2:3]
	s_cbranch_execz .LBB0_2885
	v_mov_b32_e32 v121, 0

; template <int M>
; __device__ __forceinline__ void hy_filter_spectra(LAS vf2* X, const int tid_in, const float* hfa, const float* hba, const float* hfb, const float* hbb, vf2* FSa, vf2* FSb) {
;     ...
;         for (int j = 0; j < N / NTHR; ++j) { const int i = tid + NTHR * j; if (i < L) { va[j] = hfa[i]; vb[j] = hfb[i]; } else if (i == L) { va[j] = 0.f; vb[j] = 0.f; } else { va[j] = hba[N - i]; vb[j] = hbb[N - i]; } }
.LBB0_2891:
	s_andn2_saveexec_b64 s[2:3], s[2:3]
	s_cbranch_execz .LBB0_2893
	v_mov_b32_e32 v127, 0

; template <int M>
; __device__ __forceinline__ void hy_filter_spectra(LAS vf2* X, const int tid_in, const float* hfa, const float* hba, const float* hfb, const float* hbb, vf2* FSa, vf2* FSb) {
;     ...
;     { float va[N / NTHR], vb[N / NTHR];
; #pragma unroll
;         for (int j = 0; j < N / NTHR; ++j) { const int i = tid + NTHR * j; if (i < L) { va[j] = hfa[i]; vb[j] = hfb[i]; } else if (i == L) { va[j] = 0.f; vb[j] = 0.f; } else { va[j] = hba[N - i]; vb[j] = hbb[N - i]; } }
; #pragma unroll
;         for (int j = 0; j < N / NTHR; ++j) { const int i = tid + NTHR * j; X[i + (i >> 4)] = (vf2){va[j], vb[j]}; } }
.LBB0_2899:
	s_andn2_saveexec_b64 s[2:3], s[2:3]
	s_cbranch_execz .LBB0_2901
	v_mov_b32_e32 v131, 0

; template <int M>
; __device__ __forceinline__ void hy_filter_spectra(LAS vf2* X, const int tid_in, const float* hfa, const float* hba, const float* hfb, const float* hbb, vf2* FSa, vf2* FSb) {
;     ...
;     { float va[N / NTHR], vb[N / NTHR];
; #pragma unroll
;         for (int j = 0; j < N / NTHR; ++j) { const int i = tid + NTHR * j; if (i < L) { va[j] = hfa[i]; vb[j] = hfb[i]; } else if (i == L) { va[j] = 0.f; vb[j] = 0.f; } else { va[j] = hba[N - i]; vb[j] = hbb[N - i]; } }
; #pragma unroll
;         for (int j = 0; j < N / NTHR; ++j) { const int i = tid + NTHR * j; X[i + (i >> 4)] = (vf2){va[j], vb[j]}; } }
.LBB0_2907:
	s_andn2_saveexec_b64 s[2:3], s[2:3]
	s_cbranch_execz .LBB0_2909
	v_mov_b32_e32 v135, 0

; template <int M>
; __device__ __forceinline__ void hy_filter_spectra(LAS vf2* X, const int tid_in, const float* hfa, const float* hba, const float* hfb, const float* hbb, vf2* FSa, vf2* FSb) {
;     ...
;     { float va[N / NTHR], vb[N / NTHR];
; #pragma unroll
;         for (int j = 0; j < N / NTHR; ++j) { const int i = tid + NTHR * j; if (i < L) { va[j] = hfa[i]; vb[j] = hfb[i]; } else if (i == L) { va[j] = 0.f; vb[j] = 0.f; } else { va[j] = hba[N - i]; vb[j] = hbb[N - i]; } }
; #pragma unroll
;         for (int j = 0; j < N / NTHR; ++j) { const int i = tid + NTHR * j; X[i + (i >> 4)] = (vf2){va[j], vb[j]}; } }
.LBB0_2915:
	s_andn2_saveexec_b64 s[2:3], s[2:3]
	s_cbranch_execz .LBB0_2917
	v_mov_b32_e32 v139, 0

; template <int M>
; __device__ __forceinline__ void hy_filter_spectra(LAS vf2* X, const int tid_in, const float* hfa, const float* hba, const float* hfb, const float* hbb, vf2* FSa, vf2* FSb) {
;     ...
;     { float va[N / NTHR], vb[N / NTHR];
; #pragma unroll
;         for (int j = 0; j < N / NTHR; ++j) { const int i = tid + NTHR * j; if (i < L) { va[j] = hfa[i]; vb[j] = hfb[i]; } else if (i == L) { va[j] = 0.f; vb[j] = 0.f; } else { va[j] = hba[N - i]; vb[j] = hbb[N - i]; } }
; #pragma unroll
;         for (int j = 0; j < N / NTHR; ++j) { const int i = tid + NTHR * j; X[i + (i >> 4)] = (vf2){va[j], vb[j]}; } }
.LBB0_2923:
	s_andn2_saveexec_b64 s[2:3], s[2:3]
	s_cbranch_execz .LBB0_2925
	v_mov_b32_e32 v143, 0

; template <int M>
; __device__ __forceinline__ void hy_filter_spectra(LAS vf2* X, const int tid_in, const float* hfa, const float* hba, const float* hfb, const float* hbb, vf2* FSa, vf2* FSb) {
;     ...
;     { float va[N / NTHR], vb[N / NTHR];
; #pragma unroll
;         for (int j = 0; j < N / NTHR; ++j) { const int i = tid + NTHR * j; if (i < L) { va[j] = hfa[i]; vb[j] = hfb[i]; } else if (i == L) { va[j] = 0.f; vb[j] = 0.f; } else { va[j] = hba[N - i]; vb[j] = hbb[N - i]; } }
; #pragma unroll
;         for (int j = 0; j < N / NTHR; ++j) { const int i = tid + NTHR * j; X[i + (i >> 4)] = (vf2){va[j], vb[j]}; } }
.LBB0_2931:
	s_andn2_saveexec_b64 s[2:3], s[2:3]
	s_cbranch_execz .LBB0_2933
	v_mov_b32_e32 v147, 0

; template <int M>
; __device__ __forceinline__ void hy_filter_spectra(LAS vf2* X, const int tid_in, const float* hfa, const float* hba, const float* hfb, const float* hbb, vf2* FSa, vf2* FSb) {
;     ...
;     { float va[N / NTHR], vb[N / NTHR];
; #pragma unroll
;         for (int j = 0; j < N / NTHR; ++j) { const int i = tid + NTHR * j; if (i < L) { va[j] = hfa[i]; vb[j] = hfb[i]; } else if (i == L) { va[j] = 0.f; vb[j] = 0.f; } else { va[j] = hba[N - i]; vb[j] = hbb[N - i]; } }
; #pragma unroll
;         for (int j = 0; j < N / NTHR; ++j) { const int i = tid + NTHR * j; X[i + (i >> 4)] = (vf2){va[j], vb[j]}; } }
.LBB0_2939:
	s_andn2_saveexec_b64 s[2:3], s[2:3]
	s_cbranch_execz .LBB0_2941
	v_mov_b32_e32 v151, 0

; template <int M>
; __device__ __forceinline__ void hy_filter_spectra(LAS vf2* X, const int tid_in, const float* hfa, const float* hba, const float* hfb, const float* hbb, vf2* FSa, vf2* FSb) {
;     ...
;     { float va[N / NTHR], vb[N / NTHR];
; #pragma unroll
;         for (int j = 0; j < N / NTHR; ++j) { const int i = tid + NTHR * j; if (i < L) { va[j] = hfa[i]; vb[j] = hfb[i]; } else if (i == L) { va[j] = 0.f; vb[j] = 0.f; } else { va[j] = hba[N - i]; vb[j] = hbb[N - i]; } }
; #pragma unroll
;         for (int j = 0; j < N / NTHR; ++j) { const int i = tid + NTHR * j; X[i + (i >> 4)] = (vf2){va[j], vb[j]}; } }
.LBB0_2947:
	s_andn2_saveexec_b64 s[2:3], s[2:3]
	s_cbranch_execz .LBB0_2949
	v_mov_b32_e32 v155, 0

; template <int M>
; __device__ __forceinline__ void hy_filter_spectra(LAS vf2* X, const int tid_in, const float* hfa, const float* hba, const float* hfb, const float* hbb, vf2* FSa, vf2* FSb) {
;     ...
;     { float va[N / NTHR], vb[N / NTHR];
; #pragma unroll
;         for (int j = 0; j < N / NTHR; ++j) { const int i = tid + NTHR * j; if (i < L) { va[j] = hfa[i]; vb[j] = hfb[i]; } else if (i == L) { va[j] = 0.f; vb[j] = 0.f; } else { va[j] = hba[N - i]; vb[j] = hbb[N - i]; } }
; #pragma unroll
;         for (int j = 0; j < N / NTHR; ++j) { const int i = tid + NTHR * j; X[i + (i >> 4)] = (vf2){va[j], vb[j]}; } }
.LBB0_2955:
	s_andn2_saveexec_b64 s[2:3], s[2:3]
	s_cbranch_execz .LBB0_2957
	v_mov_b32_e32 v159, 0

; template <int M>
; __device__ __forceinline__ void hy_filter_spectra(LAS vf2* X, const int tid_in, const float* hfa, const float* hba, const float* hfb, const float* hbb, vf2* FSa, vf2* FSb) {
;     ...
;     { float va[N / NTHR], vb[N / NTHR];
; #pragma unroll
;         for (int j = 0; j < N / NTHR; ++j) { const int i = tid + NTHR * j; if (i < L) { va[j] = hfa[i]; vb[j] = hfb[i]; } else if (i == L) { va[j] = 0.f; vb[j] = 0.f; } else { va[j] = hba[N - i]; vb[j] = hbb[N - i]; } }
; #pragma unroll
;         for (int j = 0; j < N / NTHR; ++j) { const int i = tid + NTHR * j; X[i + (i >> 4)] = (vf2){va[j], vb[j]}; } }
.LBB0_2963:
	s_andn2_saveexec_b64 s[2:3], s[2:3]
	s_cbranch_execz .LBB0_2965
	v_mov_b32_e32 v67, 0

; template <int M>
; __device__ __forceinline__ void hy_filter_spectra(LAS vf2* X, const int tid_in, const float* hfa, const float* hba, const float* hfb, const float* hbb, vf2* FSa, vf2* FSb) {
;     ...
;     { float va[N / NTHR], vb[N / NTHR];
; #pragma unroll
;         for (int j = 0; j < N / NTHR; ++j) { const int i = tid + NTHR * j; if (i < L) { va[j] = hfa[i]; vb[j] = hfb[i]; } else if (i == L) { va[j] = 0.f; vb[j] = 0.f; } else { va[j] = hba[N - i]; vb[j] = hbb[N - i]; } }
; #pragma unroll
;         for (int j = 0; j < N / NTHR; ++j) { const int i = tid + NTHR * j; X[i + (i >> 4)] = (vf2){va[j], vb[j]}; } }
.LBB0_2971:
	s_andn2_saveexec_b64 s[2:3], s[2:3]
	s_cbranch_execz .LBB0_2973
	v_mov_b32_e32 v69, 0

; template <int M>
; __device__ __forceinline__ void hy_filter_spectra(LAS vf2* X, const int tid_in, const float* hfa, const float* hba, const float* hfb, const float* hbb, vf2* FSa, vf2* FSb) {
;     ...
;     { float va[N / NTHR], vb[N / NTHR];
; #pragma unroll
;         for (int j = 0; j < N / NTHR; ++j) { const int i = tid + NTHR * j; if (i < L) { va[j] = hfa[i]; vb[j] = hfb[i]; } else if (i == L) { va[j] = 0.f; vb[j] = 0.f; } else { va[j] = hba[N - i]; vb[j] = hbb[N - i]; } }
; #pragma unroll
;         for (int j = 0; j < N / NTHR; ++j) { const int i = tid + NTHR * j; X[i + (i >> 4)] = (vf2){va[j], vb[j]}; } }
.LBB0_2979:
	s_andn2_saveexec_b64 s[2:3], s[2:3]
	s_cbranch_execz .LBB0_2981
	v_mov_b32_e32 v73, 0

; template <int M>
; __device__ __forceinline__ void hy_filter_spectra(LAS vf2* X, const int tid_in, const float* hfa, const float* hba, const float* hfb, const float* hbb, vf2* FSa, vf2* FSb) {
;     ...
;     { float va[N / NTHR], vb[N / NTHR];
; #pragma unroll
;         for (int j = 0; j < N / NTHR; ++j) { const int i = tid + NTHR * j; if (i < L) { va[j] = hfa[i]; vb[j] = hfb[i]; } else if (i == L) { va[j] = 0.f; vb[j] = 0.f; } else { va[j] = hba[N - i]; vb[j] = hbb[N - i]; } }
; #pragma unroll
;         for (int j = 0; j < N / NTHR; ++j) { const int i = tid + NTHR * j; X[i + (i >> 4)] = (vf2){va[j], vb[j]}; } }
.LBB0_2987:
	s_andn2_saveexec_b64 s[2:3], s[2:3]
	s_cbranch_execz .LBB0_2989
	v_mov_b32_e32 v77, 0

; template <int M>
; __device__ __forceinline__ void hy_filter_spectra(LAS vf2* X, const int tid_in, const float* hfa, const float* hba, const float* hfb, const float* hbb, vf2* FSa, vf2* FSb) {
;     ...
;     { float va[N / NTHR], vb[N / NTHR];
; #pragma unroll
;         for (int j = 0; j < N / NTHR; ++j) { const int i = tid + NTHR * j; if (i < L) { va[j] = hfa[i]; vb[j] = hfb[i]; } else if (i == L) { va[j] = 0.f; vb[j] = 0.f; } else { va[j] = hba[N - i]; vb[j] = hbb[N - i]; } }
; #pragma unroll
;         for (int j = 0; j < N / NTHR; ++j) { const int i = tid + NTHR * j; X[i + (i >> 4)] = (vf2){va[j], vb[j]}; } }
.LBB0_2995:
	s_andn2_saveexec_b64 s[2:3], s[2:3]
	s_cbranch_execz .LBB0_2997
	v_mov_b32_e32 v81, 0

; template <int M>
; __device__ __forceinline__ void hy_filter_spectra(LAS vf2* X, const int tid_in, const float* hfa, const float* hba, const float* hfb, const float* hbb, vf2* FSa, vf2* FSb) {
;     ...
;     { float va[N / NTHR], vb[N / NTHR];
; #pragma unroll
;         for (int j = 0; j < N / NTHR; ++j) { const int i = tid + NTHR * j; if (i < L) { va[j] = hfa[i]; vb[j] = hfb[i]; } else if (i == L) { va[j] = 0.f; vb[j] = 0.f; } else { va[j] = hba[N - i]; vb[j] = hbb[N - i]; } }
; #pragma unroll
;         for (int j = 0; j < N / NTHR; ++j) { const int i = tid + NTHR * j; X[i + (i >> 4)] = (vf2){va[j], vb[j]}; } }
.LBB0_3003:
	s_andn2_saveexec_b64 s[2:3], s[2:3]
	s_cbranch_execz .LBB0_3005
	v_mov_b32_e32 v85, 0

; template <int M>
; __device__ __forceinline__ void hy_filter_spectra(LAS vf2* X, const int tid_in, const float* hfa, const float* hba, const float* hfb, const float* hbb, vf2* FSa, vf2* FSb) {
;     ...
;     { float va[N / NTHR], vb[N / NTHR];
; #pragma unroll
;         for (int j = 0; j < N / NTHR; ++j) { const int i = tid + NTHR * j; if (i < L) { va[j] = hfa[i]; vb[j] = hfb[i]; } else if (i == L) { va[j] = 0.f; vb[j] = 0.f; } else { va[j] = hba[N - i]; vb[j] = hbb[N - i]; } }
; #pragma unroll
;         for (int j = 0; j < N / NTHR; ++j) { const int i = tid + NTHR * j; X[i + (i >> 4)] = (vf2){va[j], vb[j]}; } }
.LBB0_3067:
	s_andn2_saveexec_b64 s[58:59], s[58:59]
	s_cbranch_execz .LBB0_3069
	v_mov_b32_e32 v31, 0

; template <int M>
; __device__ __forceinline__ void hy_filter_spectra(LAS vf2* X, const int tid_in, const float* hfa, const float* hba, const float* hfb, const float* hbb, vf2* FSa, vf2* FSb) {
;     ...
;     { float va[N / NTHR], vb[N / NTHR];
; #pragma unroll
;         for (int j = 0; j < N / NTHR; ++j) { const int i = tid + NTHR * j; if (i < L) { va[j] = hfa[i]; vb[j] = hfb[i]; } else if (i == L) { va[j] = 0.f; vb[j] = 0.f; } else { va[j] = hba[N - i]; vb[j] = hbb[N - i]; } }
; #pragma unroll
;         for (int j = 0; j < N / NTHR; ++j) { const int i = tid + NTHR * j; X[i + (i >> 4)] = (vf2){va[j], vb[j]}; } }
.LBB0_3075:
	s_andn2_saveexec_b64 s[58:59], s[58:59]
	s_cbranch_execz .LBB0_3077
	v_mov_b32_e32 v17, 0

; template <int M>
; __device__ __forceinline__ void hy_filter_spectra(LAS vf2* X, const int tid_in, const float* hfa, const float* hba, const float* hfb, const float* hbb, vf2* FSa, vf2* FSb) {
;     ...
;     { float va[N / NTHR], vb[N / NTHR];
; #pragma unroll
;         for (int j = 0; j < N / NTHR; ++j) { const int i = tid + NTHR * j; if (i < L) { va[j] = hfa[i]; vb[j] = hfb[i]; } else if (i == L) { va[j] = 0.f; vb[j] = 0.f; } else { va[j] = hba[N - i]; vb[j] = hbb[N - i]; } }
; #pragma unroll
;         for (int j = 0; j < N / NTHR; ++j) { const int i = tid + NTHR * j; X[i + (i >> 4)] = (vf2){va[j], vb[j]}; } }
.LBB0_3078:
	s_andn2_saveexec_b64 s[56:57], s[56:57]
	s_cbranch_execz .LBB0_3080
	v_ashrrev_i32_e32 v33, 31, v32
	v_lshlrev_b64 v[34:35], 2, v[32:33]
	v_lshl_add_u64 v[16:17], s[0:1], 0, v[34:35]
	v_lshl_add_u64 v[34:35], s[2:3], 0, v[34:35]
	global_load_dword v16, v[16:17], off
	s_nop 0
	global_load_dword v17, v[34:35], off

; template <int M>
; __device__ __forceinline__ void hy_filter_spectra(LAS vf2* X, const int tid_in, const float* hfa, const float* hba, const float* hfb, const float* hbb, vf2* FSa, vf2* FSb) {
;     ...
;     { float va[N / NTHR], vb[N / NTHR];
; #pragma unroll
;         for (int j = 0; j < N / NTHR; ++j) { const int i = tid + NTHR * j; if (i < L) { va[j] = hfa[i]; vb[j] = hfb[i]; } else if (i == L) { va[j] = 0.f; vb[j] = 0.f; } else { va[j] = hba[N - i]; vb[j] = hbb[N - i]; } }
; #pragma unroll
;         for (int j = 0; j < N / NTHR; ++j) { const int i = tid + NTHR * j; X[i + (i >> 4)] = (vf2){va[j], vb[j]}; } }
.LBB0_3083:
	s_andn2_saveexec_b64 s[58:59], s[58:59]
	s_cbranch_execz .LBB0_3085
	v_mov_b32_e32 v37, 0

; template <int M>
; __device__ __forceinline__ void hy_filter_spectra(LAS vf2* X, const int tid_in, const float* hfa, const float* hba, const float* hfb, const float* hbb, vf2* FSa, vf2* FSb) {
;     ...
;     { float va[N / NTHR], vb[N / NTHR];
; #pragma unroll
;         for (int j = 0; j < N / NTHR; ++j) { const int i = tid + NTHR * j; if (i < L) { va[j] = hfa[i]; vb[j] = hfb[i]; } else if (i == L) { va[j] = 0.f; vb[j] = 0.f; } else { va[j] = hba[N - i]; vb[j] = hbb[N - i]; } }
; #pragma unroll
;         for (int j = 0; j < N / NTHR; ++j) { const int i = tid + NTHR * j; X[i + (i >> 4)] = (vf2){va[j], vb[j]}; } }
.LBB0_3091:
	s_andn2_saveexec_b64 s[58:59], s[58:59]
	s_cbranch_execz .LBB0_3093
	v_mov_b32_e32 v33, 0

; template <int M>
; __device__ __forceinline__ void hy_filter_spectra(LAS vf2* X, const int tid_in, const float* hfa, const float* hba, const float* hfb, const float* hbb, vf2* FSa, vf2* FSb) {
;     ...
;     { float va[N / NTHR], vb[N / NTHR];
; #pragma unroll
;         for (int j = 0; j < N / NTHR; ++j) { const int i = tid + NTHR * j; if (i < L) { va[j] = hfa[i]; vb[j] = hfb[i]; } else if (i == L) { va[j] = 0.f; vb[j] = 0.f; } else { va[j] = hba[N - i]; vb[j] = hbb[N - i]; } }
; #pragma unroll
;         for (int j = 0; j < N / NTHR; ++j) { const int i = tid + NTHR * j; X[i + (i >> 4)] = (vf2){va[j], vb[j]}; } }
.LBB0_3099:
	s_andn2_saveexec_b64 s[58:59], s[58:59]
	s_cbranch_execz .LBB0_3101
	v_mov_b32_e32 v35, 0

; template <int M>
; __device__ __forceinline__ void hy_filter_spectra(LAS vf2* X, const int tid_in, const float* hfa, const float* hba, const float* hfb, const float* hbb, vf2* FSa, vf2* FSb) {
;     ...
;     { float va[N / NTHR], vb[N / NTHR];
; #pragma unroll
;         for (int j = 0; j < N / NTHR; ++j) { const int i = tid + NTHR * j; if (i < L) { va[j] = hfa[i]; vb[j] = hfb[i]; } else if (i == L) { va[j] = 0.f; vb[j] = 0.f; } else { va[j] = hba[N - i]; vb[j] = hbb[N - i]; } }
; #pragma unroll
;         for (int j = 0; j < N / NTHR; ++j) { const int i = tid + NTHR * j; X[i + (i >> 4)] = (vf2){va[j], vb[j]}; } }
.LBB0_3107:
	s_andn2_saveexec_b64 s[58:59], s[58:59]
	s_cbranch_execz .LBB0_3109
	v_mov_b32_e32 v39, 0

; template <int M>
; __device__ __forceinline__ void hy_filter_spectra(LAS vf2* X, const int tid_in, const float* hfa, const float* hba, const float* hfb, const float* hbb, vf2* FSa, vf2* FSb) {
;     ...
;     { float va[N / NTHR], vb[N / NTHR];
; #pragma unroll
;         for (int j = 0; j < N / NTHR; ++j) { const int i = tid + NTHR * j; if (i < L) { va[j] = hfa[i]; vb[j] = hfb[i]; } else if (i == L) { va[j] = 0.f; vb[j] = 0.f; } else { va[j] = hba[N - i]; vb[j] = hbb[N - i]; } }
; #pragma unroll
;         for (int j = 0; j < N / NTHR; ++j) { const int i = tid + NTHR * j; X[i + (i >> 4)] = (vf2){va[j], vb[j]}; } }
.LBB0_3115:
	s_andn2_saveexec_b64 s[58:59], s[58:59]
	s_cbranch_execz .LBB0_3117
	v_mov_b32_e32 v41, 0

; template <int M>
; __device__ __forceinline__ void hy_filter_spectra(LAS vf2* X, const int tid_in, const float* hfa, const float* hba, const float* hfb, const float* hbb, vf2* FSa, vf2* FSb) {
;     ...
;     { float va[N / NTHR], vb[N / NTHR];
; #pragma unroll
;         for (int j = 0; j < N / NTHR; ++j) { const int i = tid + NTHR * j; if (i < L) { va[j] = hfa[i]; vb[j] = hfb[i]; } else if (i == L) { va[j] = 0.f; vb[j] = 0.f; } else { va[j] = hba[N - i]; vb[j] = hbb[N - i]; } }
; #pragma unroll
;         for (int j = 0; j < N / NTHR; ++j) { const int i = tid + NTHR * j; X[i + (i >> 4)] = (vf2){va[j], vb[j]}; } }
.LBB0_3123:
	s_andn2_saveexec_b64 s[58:59], s[58:59]
	s_cbranch_execz .LBB0_3125
	v_mov_b32_e32 v43, 0

; template <int M>
; __device__ __forceinline__ void hy_filter_spectra(LAS vf2* X, const int tid_in, const float* hfa, const float* hba, const float* hfb, const float* hbb, vf2* FSa, vf2* FSb) {
;     ...
;     { float va[N / NTHR], vb[N / NTHR];
; #pragma unroll
;         for (int j = 0; j < N / NTHR; ++j) { const int i = tid + NTHR * j; if (i < L) { va[j] = hfa[i]; vb[j] = hfb[i]; } else if (i == L) { va[j] = 0.f; vb[j] = 0.f; } else { va[j] = hba[N - i]; vb[j] = hbb[N - i]; } }
; #pragma unroll
;         for (int j = 0; j < N / NTHR; ++j) { const int i = tid + NTHR * j; X[i + (i >> 4)] = (vf2){va[j], vb[j]}; } }
.LBB0_3131:
	s_andn2_saveexec_b64 s[58:59], s[58:59]
	s_cbranch_execz .LBB0_3133
	v_mov_b32_e32 v45, 0

; template <int M>
; __device__ __forceinline__ void hy_filter_spectra(LAS vf2* X, const int tid_in, const float* hfa, const float* hba, const float* hfb, const float* hbb, vf2* FSa, vf2* FSb) {
;     ...
;     { float va[N / NTHR], vb[N / NTHR];
; #pragma unroll
;         for (int j = 0; j < N / NTHR; ++j) { const int i = tid + NTHR * j; if (i < L) { va[j] = hfa[i]; vb[j] = hfb[i]; } else if (i == L) { va[j] = 0.f; vb[j] = 0.f; } else { va[j] = hba[N - i]; vb[j] = hbb[N - i]; } }
; #pragma unroll
;         for (int j = 0; j < N / NTHR; ++j) { const int i = tid + NTHR * j; X[i + (i >> 4)] = (vf2){va[j], vb[j]}; } }
.LBB0_3139:
	s_andn2_saveexec_b64 s[58:59], s[58:59]
	s_cbranch_execz .LBB0_3141
	v_mov_b32_e32 v47, 0

; template <int M>
; __device__ __forceinline__ void hy_filter_spectra(LAS vf2* X, const int tid_in, const float* hfa, const float* hba, const float* hfb, const float* hbb, vf2* FSa, vf2* FSb) {
;     ...
;     { float va[N / NTHR], vb[N / NTHR];
; #pragma unroll
;         for (int j = 0; j < N / NTHR; ++j) { const int i = tid + NTHR * j; if (i < L) { va[j] = hfa[i]; vb[j] = hfb[i]; } else if (i == L) { va[j] = 0.f; vb[j] = 0.f; } else { va[j] = hba[N - i]; vb[j] = hbb[N - i]; } }
; #pragma unroll
;         for (int j = 0; j < N / NTHR; ++j) { const int i = tid + NTHR * j; X[i + (i >> 4)] = (vf2){va[j], vb[j]}; } }
.LBB0_3147:
	s_andn2_saveexec_b64 s[58:59], s[58:59]
	s_cbranch_execz .LBB0_3149
	v_mov_b32_e32 v49, 0

; template <int M>
; __device__ __forceinline__ void hy_filter_spectra(LAS vf2* X, const int tid_in, const float* hfa, const float* hba, const float* hfb, const float* hbb, vf2* FSa, vf2* FSb) {
;     ...
;     { float va[N / NTHR], vb[N / NTHR];
; #pragma unroll
;         for (int j = 0; j < N / NTHR; ++j) { const int i = tid + NTHR * j; if (i < L) { va[j] = hfa[i]; vb[j] = hfb[i]; } else if (i == L) { va[j] = 0.f; vb[j] = 0.f; } else { va[j] = hba[N - i]; vb[j] = hbb[N - i]; } }
; #pragma unroll
;         for (int j = 0; j < N / NTHR; ++j) { const int i = tid + NTHR * j; X[i + (i >> 4)] = (vf2){va[j], vb[j]}; } }
.LBB0_3155:
	s_andn2_saveexec_b64 s[58:59], s[58:59]
	s_cbranch_execz .LBB0_3157
	v_mov_b32_e32 v61, 0

; template <int M>
; __device__ __forceinline__ void hy_filter_spectra(LAS vf2* X, const int tid_in, const float* hfa, const float* hba, const float* hfb, const float* hbb, vf2* FSa, vf2* FSb) {
;     ...
;     { float va[N / NTHR], vb[N / NTHR];
; #pragma unroll
;         for (int j = 0; j < N / NTHR; ++j) { const int i = tid + NTHR * j; if (i < L) { va[j] = hfa[i]; vb[j] = hfb[i]; } else if (i == L) { va[j] = 0.f; vb[j] = 0.f; } else { va[j] = hba[N - i]; vb[j] = hbb[N - i]; } }
; #pragma unroll
;         for (int j = 0; j < N / NTHR; ++j) { const int i = tid + NTHR * j; X[i + (i >> 4)] = (vf2){va[j], vb[j]}; } }
.LBB0_3163:
	s_andn2_saveexec_b64 s[58:59], s[58:59]
	s_cbranch_execz .LBB0_3165
	v_mov_b32_e32 v63, 0

; template <int M>
; __device__ __forceinline__ void hy_filter_spectra(LAS vf2* X, const int tid_in, const float* hfa, const float* hba, const float* hfb, const float* hbb, vf2* FSa, vf2* FSb) {
;     ...
;     { float va[N / NTHR], vb[N / NTHR];
; #pragma unroll
;         for (int j = 0; j < N / NTHR; ++j) { const int i = tid + NTHR * j; if (i < L) { va[j] = hfa[i]; vb[j] = hfb[i]; } else if (i == L) { va[j] = 0.f; vb[j] = 0.f; } else { va[j] = hba[N - i]; vb[j] = hbb[N - i]; } }
; #pragma unroll
;         for (int j = 0; j < N / NTHR; ++j) { const int i = tid + NTHR * j; X[i + (i >> 4)] = (vf2){va[j], vb[j]}; } }
.LBB0_3171:
	s_andn2_saveexec_b64 s[58:59], s[58:59]
	s_cbranch_execz .LBB0_3173
	v_mov_b32_e32 v65, 0

; template <int M>
; __device__ __forceinline__ void hy_filter_spectra(LAS vf2* X, const int tid_in, const float* hfa, const float* hba, const float* hfb, const float* hbb, vf2* FSa, vf2* FSb) {
;     ...
;     { float va[N / NTHR], vb[N / NTHR];
; #pragma unroll
;         for (int j = 0; j < N / NTHR; ++j) { const int i = tid + NTHR * j; if (i < L) { va[j] = hfa[i]; vb[j] = hfb[i]; } else if (i == L) { va[j] = 0.f; vb[j] = 0.f; } else { va[j] = hba[N - i]; vb[j] = hbb[N - i]; } }
; #pragma unroll
;         for (int j = 0; j < N / NTHR; ++j) { const int i = tid + NTHR * j; X[i + (i >> 4)] = (vf2){va[j], vb[j]}; } }
.LBB0_3179:
	s_andn2_saveexec_b64 s[52:53], s[58:59]
	s_cbranch_execz .LBB0_3181
	v_mov_b32_e32 v67, 0
